# init copy loop unrolled 8x (exact 4 trips, no serial tail) on top of LN gamma/beta hoist and deep pool-fold loops
# baseline (speedup 1.0000x reference)
; DEVI void init_phase(const Params& p) {
;     ...
;   for (int idx = gt; idx < L * 256; idx += nth) {
;     const int t = idx >> 8, c = (idx & 255) * 4;
;     f32x4 v = (t < 16) ? *(const f32x4*)(p.in[1] + t * 1024 + c) : *(const f32x4*)(p.in[0] + (size_t)(t - 16) * 1024 + c);
;     if (t < 16) *(f32x4*)(hfrow(p, t) + c) = v;
;     *(u32x2*)(hb + (size_t)t * 1024 + c) = u32x2{pack2(v[0], v[1]), pack2(v[2], v[3])};
;   }
.Lmy_init_main:
	s_or_b64 exec, exec, s[0:1]
	s_add_u32 s24, s14, 0x8000
	s_addc_u32 s25, s15, 0
	v_readfirstlane_b32 s0, v6
	s_lshl_b32 s1, s48, 8
	s_lshl_b32 s16, s48, 12
	s_lshl_b32 s17, s48, 11
	s_mul_i32 s5, s1, 7
	v_lshlrev_b32_e32 v12, 4, v6
	v_lshlrev_b32_e32 v13, 3, v6
.Lmy_init_loop:
	s_add_u32 s0, s0, s5
	s_cmp_lt_u32 s0, 0x400000
	s_cbranch_scc0 .Lmy_init_tailpre
	global_load_dwordx4 v[14:17], v12, s[68:69]
	v_add_u32_e32 v8, s16, v12
	global_load_dwordx4 v[18:21], v8, s[68:69]
	v_add_u32_e32 v8, s16, v8
	global_load_dwordx4 v[22:25], v8, s[68:69]
	v_add_u32_e32 v8, s16, v8
	global_load_dwordx4 v[26:29], v8, s[68:69]
	v_add_u32_e32 v8, s16, v8
	global_load_dwordx4 v[30:33], v8, s[68:69]
	v_add_u32_e32 v8, s16, v8
	global_load_dwordx4 v[34:37], v8, s[68:69]
	v_add_u32_e32 v8, s16, v8
	global_load_dwordx4 v[38:41], v8, s[68:69]
	v_add_u32_e32 v8, s16, v8
	global_load_dwordx4 v[42:45], v8, s[68:69]
	v_add_u32_e32 v12, s16, v8
	s_waitcnt vmcnt(7)
	v_cvt_pk_bf16_f32 v14, v14, v15
	v_cvt_pk_bf16_f32 v15, v16, v17
	s_waitcnt vmcnt(6)
	v_cvt_pk_bf16_f32 v18, v18, v19
	v_cvt_pk_bf16_f32 v19, v20, v21
	s_waitcnt vmcnt(5)
	v_cvt_pk_bf16_f32 v22, v22, v23
	v_cvt_pk_bf16_f32 v23, v24, v25
	s_waitcnt vmcnt(4)
	v_cvt_pk_bf16_f32 v26, v26, v27
	v_cvt_pk_bf16_f32 v27, v28, v29
	s_waitcnt vmcnt(3)
	v_cvt_pk_bf16_f32 v30, v30, v31
	v_cvt_pk_bf16_f32 v31, v32, v33
	s_waitcnt vmcnt(2)
	v_cvt_pk_bf16_f32 v34, v34, v35
	v_cvt_pk_bf16_f32 v35, v36, v37
	s_waitcnt vmcnt(1)
	v_cvt_pk_bf16_f32 v38, v38, v39
	v_cvt_pk_bf16_f32 v39, v40, v41
	s_waitcnt vmcnt(0)
	v_cvt_pk_bf16_f32 v42, v42, v43
	v_cvt_pk_bf16_f32 v43, v44, v45
	global_store_dwordx2 v13, v[14:15], s[24:25]
	v_add_u32_e32 v13, s17, v13
	global_store_dwordx2 v13, v[18:19], s[24:25]
	v_add_u32_e32 v13, s17, v13
	global_store_dwordx2 v13, v[22:23], s[24:25]
	v_add_u32_e32 v13, s17, v13
	global_store_dwordx2 v13, v[26:27], s[24:25]
	v_add_u32_e32 v13, s17, v13
	global_store_dwordx2 v13, v[30:31], s[24:25]
	v_add_u32_e32 v13, s17, v13
	global_store_dwordx2 v13, v[34:35], s[24:25]
	v_add_u32_e32 v13, s17, v13
	global_store_dwordx2 v13, v[38:39], s[24:25]
	v_add_u32_e32 v13, s17, v13
	global_store_dwordx2 v13, v[42:43], s[24:25]
	v_add_u32_e32 v13, s17, v13
	s_add_u32 s0, s0, s1
	s_branch .Lmy_init_loop
